# even in-proj epilogue: the four row-statistic loads of each row half issued together with counted waits (were load / vmcnt(0) / reduce x4, twice per tile)
# speedup vs baseline: 1.0049x; 1.0023x over previous
.LBB0_525:
	s_lshl_b32 s10, s14, 8
	s_add_i32 s10, s10, s38
	v_add_u32_e32 v194, s10, v245
	s_lshl_b32 s10, s18, 8
	s_or_b32 s10, s10, s39
	v_lshlrev_b32_e32 v196, 3, v197
	s_lshl_b64 s[8:9], s[8:9], 2
	v_add_u32_e32 v200, s10, v196
	s_add_u32 s8, s74, s8
	s_addc_u32 s9, s75, s9
	v_ashrrev_i32_e32 v201, 31, v200
	v_lshl_add_u64 v[198:199], v[200:201], 2, s[8:9]
	s_cmp_eq_u32 s18, 9
	s_mov_b64 s[8:9], -1
	s_mov_b32 s54, 0x8000
	s_cbranch_scc1 .LBB0_679
	v_lshlrev_b32_e32 v146, 2, v197
	v_ashrrev_i32_e32 v147, 31, v146
	v_ashrrev_i32_e32 v195, 31, v194
	v_lshl_add_u64 v[206:207], v[146:147], 2, s[68:69]
	v_lshlrev_b64 v[146:147], 6, v[194:195]
	v_lshl_add_u64 v[146:147], v[206:207], 0, v[146:147]
	global_load_dwordx4 v[90:93], v[198:199], off offset:16
	global_load_dwordx4 v[94:97], v[198:199], off
	global_load_dwordx4 v[82:85], v[198:199], off offset:528
	global_load_dwordx4 v[86:89], v[198:199], off offset:512
	v_add_u32_e32 v216, 16, v194
	global_load_dwordx4 v[146:149], v[146:147], off
	v_ashrrev_i32_e32 v217, 31, v216
	v_add_u32_e32 v210, 32, v194
	v_ashrrev_i32_e32 v211, 31, v210
	v_add_u32_e32 v208, 48, v194
	v_ashrrev_i32_e32 v209, 31, v208
	s_cmp_gt_i32 s14, 31
	s_cselect_b64 s[12:13], -1, 0
	s_add_i32 s19, s18, -10
	s_cmp_lt_u32 s19, 8
	s_cselect_b64 s[8:9], -1, 0
	s_and_b64 s[14:15], s[12:13], s[8:9]
	v_and_b32_e32 v152, 8, v196
	v_and_b32_e32 v244, 63, v245
	s_and_b64 vcc, exec, s[14:15]
	v_lshlrev_b32_e32 v202, 2, v152
	v_lshlrev_b64 v[166:167], 6, v[216:217]
	v_lshl_add_u64 v[166:167], v[206:207], 0, v[166:167]
	global_load_dwordx4 v[154:157], v[166:167], off
	v_lshlrev_b64 v[168:169], 6, v[210:211]
	v_lshl_add_u64 v[168:169], v[206:207], 0, v[168:169]
	global_load_dwordx4 v[158:161], v[168:169], off
	v_lshlrev_b64 v[218:219], 6, v[208:209]
	v_lshl_add_u64 v[218:219], v[206:207], 0, v[218:219]
	global_load_dwordx4 v[184:187], v[218:219], off
	s_waitcnt vmcnt(3)
	v_mov_b32_e32 v150, v147
	v_mov_b32_e32 v151, v148
	v_mov_b32_e32 v147, v149
	v_pk_add_f32 v[146:147], v[150:151], v[146:147]
	s_nop 0
	v_pk_add_f32 v[146:147], v[146:147], v[146:147] op_sel:[0,1] op_sel_hi:[1,0]
	s_nop 0
	v_mov_b32_e32 v147, v146
	s_nop 1
	v_permlane16_swap_b32_e32 v146, v147
	v_add_f32_e32 v163, v146, v147
	v_mov_b32_e32 v165, v163
	s_nop 1
	v_permlane32_swap_b32_e32 v163, v165
	s_waitcnt vmcnt(2)
	v_mov_b32_e32 v146, v154
	v_mov_b32_e32 v147, v155
	v_mov_b32_e32 v148, v156
	v_mov_b32_e32 v149, v157
	v_mov_b32_e32 v150, v147
	v_mov_b32_e32 v151, v148
	v_mov_b32_e32 v147, v149
	v_pk_add_f32 v[146:147], v[150:151], v[146:147]
	s_nop 0
	v_pk_add_f32 v[146:147], v[146:147], v[146:147] op_sel:[0,1] op_sel_hi:[1,0]
	s_nop 0
	v_mov_b32_e32 v147, v146
	s_nop 1
	v_permlane16_swap_b32_e32 v146, v147
	v_add_f32_e32 v162, v146, v147
	v_mov_b32_e32 v164, v162
	s_nop 1
	v_permlane32_swap_b32_e32 v162, v164
	s_waitcnt vmcnt(1)
	v_mov_b32_e32 v146, v158
	v_mov_b32_e32 v147, v159
	v_mov_b32_e32 v148, v160
	v_mov_b32_e32 v149, v161
	v_mov_b32_e32 v150, v147
	v_mov_b32_e32 v151, v148
	v_mov_b32_e32 v147, v149
	v_pk_add_f32 v[146:147], v[150:151], v[146:147]
	s_nop 0
	v_pk_add_f32 v[146:147], v[146:147], v[146:147] op_sel:[0,1] op_sel_hi:[1,0]
	s_nop 0
	v_mov_b32_e32 v147, v146
	s_nop 1
	v_permlane16_swap_b32_e32 v146, v147
	v_add_f32_e32 v213, v146, v147
	v_mov_b32_e32 v215, v213
	s_nop 1
	v_permlane32_swap_b32_e32 v213, v215
	s_waitcnt vmcnt(0)
	v_mov_b32_e32 v146, v184
	v_mov_b32_e32 v147, v185
	v_mov_b32_e32 v148, v186
	v_mov_b32_e32 v149, v187
	v_mov_b32_e32 v150, v147
	v_mov_b32_e32 v151, v148
	v_mov_b32_e32 v147, v149
	v_pk_add_f32 v[146:147], v[150:151], v[146:147]
	s_nop 0
	v_pk_add_f32 v[146:147], v[146:147], v[146:147] op_sel:[0,1] op_sel_hi:[1,0]
	s_nop 0
	v_mov_b32_e32 v147, v146
	s_nop 1
	v_permlane16_swap_b32_e32 v146, v147
	v_add_f32_e32 v212, v146, v147
	v_mov_b32_e32 v214, v212
	s_nop 1
	v_permlane32_swap_b32_e32 v212, v214
	s_cbranch_vccz .LBB0_528
	v_bfe_u32 v146, v194, 6, 4
	v_cndmask_b32_e64 v146, v244, v146, s[4:5]
	v_lshlrev_b32_e32 v146, 6, v146
	v_mov_b32_e32 v147, v0
	v_lshl_add_u64 v[146:147], s[52:53], 0, v[146:147]
	v_mov_b32_e32 v203, v0
	v_lshl_add_u64 v[154:155], v[146:147], 0, v[202:203]
	s_mov_b64 s[8:9], 0x1000
	global_load_dwordx4 v[150:153], v[154:155], off
	global_load_dwordx4 v[146:149], v[154:155], off offset:16
	v_lshl_add_u64 v[156:157], v[154:155], 0, s[8:9]
	v_add_co_u32_e32 v154, vcc, 0x1000, v154
	s_nop 1
	v_addc_co_u32_e32 v155, vcc, 0, v155, vcc
	global_load_dwordx4 v[158:161], v[154:155], off
	s_nop 0
	global_load_dwordx4 v[154:157], v[156:157], off offset:16
	s_branch .LBB0_529

.LBB0_602:
	s_waitcnt vmcnt(2)
	v_add_u32_e32 v130, 0x80, v194
	v_ashrrev_i32_e32 v131, 31, v130
	v_lshlrev_b64 v[114:115], 6, v[130:131]
	v_lshl_add_u64 v[114:115], v[206:207], 0, v[114:115]
	global_load_dwordx4 v[114:117], v[114:115], off
	v_add_u32_e32 v146, 0x90, v194
	v_ashrrev_i32_e32 v147, 31, v146
	v_add_u32_e32 v140, 0xa0, v194
	v_ashrrev_i32_e32 v141, 31, v140
	v_add_u32_e32 v138, 0xb0, v194
	v_ashrrev_i32_e32 v139, 31, v138
	s_and_b64 vcc, exec, s[10:11]
	v_lshlrev_b64 v[128:129], 6, v[146:147]
	v_lshl_add_u64 v[128:129], v[206:207], 0, v[128:129]
	global_load_dwordx4 v[120:123], v[128:129], off
	v_lshlrev_b64 v[136:137], 6, v[140:141]
	v_lshl_add_u64 v[136:137], v[206:207], 0, v[136:137]
	global_load_dwordx4 v[124:127], v[136:137], off
	v_lshlrev_b64 v[152:153], 6, v[138:139]
	v_lshl_add_u64 v[152:153], v[206:207], 0, v[152:153]
	global_load_dwordx4 v[148:151], v[152:153], off
	s_waitcnt vmcnt(3)
	v_mov_b32_e32 v118, v115
	v_mov_b32_e32 v119, v116
	v_mov_b32_e32 v115, v117
	v_pk_add_f32 v[114:115], v[118:119], v[114:115]
	s_nop 0
	v_pk_add_f32 v[114:115], v[114:115], v[114:115] op_sel:[0,1] op_sel_hi:[1,0]
	s_nop 0
	v_mov_b32_e32 v115, v114
	s_nop 1
	v_permlane16_swap_b32_e32 v114, v115
	v_add_f32_e32 v133, v114, v115
	v_mov_b32_e32 v135, v133
	s_nop 1
	v_permlane32_swap_b32_e32 v133, v135
	s_waitcnt vmcnt(2)
	v_mov_b32_e32 v114, v120
	v_mov_b32_e32 v115, v121
	v_mov_b32_e32 v116, v122
	v_mov_b32_e32 v117, v123
	v_mov_b32_e32 v118, v115
	v_mov_b32_e32 v119, v116
	v_mov_b32_e32 v115, v117
	v_pk_add_f32 v[114:115], v[118:119], v[114:115]
	s_nop 0
	v_pk_add_f32 v[114:115], v[114:115], v[114:115] op_sel:[0,1] op_sel_hi:[1,0]
	s_nop 0
	v_mov_b32_e32 v115, v114
	s_nop 1
	v_permlane16_swap_b32_e32 v114, v115
	v_add_f32_e32 v132, v114, v115
	v_mov_b32_e32 v134, v132
	s_nop 1
	v_permlane32_swap_b32_e32 v132, v134
	s_waitcnt vmcnt(1)
	v_mov_b32_e32 v114, v124
	v_mov_b32_e32 v115, v125
	v_mov_b32_e32 v116, v126
	v_mov_b32_e32 v117, v127
	v_mov_b32_e32 v118, v115
	v_mov_b32_e32 v119, v116
	v_mov_b32_e32 v115, v117
	v_pk_add_f32 v[114:115], v[118:119], v[114:115]
	s_nop 0
	v_pk_add_f32 v[114:115], v[114:115], v[114:115] op_sel:[0,1] op_sel_hi:[1,0]
	s_nop 0
	v_mov_b32_e32 v115, v114
	s_nop 1
	v_permlane16_swap_b32_e32 v114, v115
	v_add_f32_e32 v143, v114, v115
	v_mov_b32_e32 v145, v143
	s_nop 1
	v_permlane32_swap_b32_e32 v143, v145
	s_waitcnt vmcnt(0)
	v_mov_b32_e32 v114, v148
	v_mov_b32_e32 v115, v149
	v_mov_b32_e32 v116, v150
	v_mov_b32_e32 v117, v151
	v_mov_b32_e32 v118, v115
	v_mov_b32_e32 v119, v116
	v_mov_b32_e32 v115, v117
	v_pk_add_f32 v[114:115], v[118:119], v[114:115]
	s_nop 0
	v_pk_add_f32 v[114:115], v[114:115], v[114:115] op_sel:[0,1] op_sel_hi:[1,0]
	s_nop 0
	v_mov_b32_e32 v115, v114
	s_nop 1
	v_permlane16_swap_b32_e32 v114, v115
	v_add_f32_e32 v142, v114, v115
	v_mov_b32_e32 v144, v142
	s_nop 1
	v_permlane32_swap_b32_e32 v142, v144
	s_cbranch_vccnz .LBB0_604
	v_bfe_u32 v114, v130, 6, 4
	v_cndmask_b32_e64 v114, v244, v114, s[4:5]
	v_lshlrev_b32_e32 v114, 6, v114
	v_mov_b32_e32 v115, v0
	v_lshl_add_u64 v[114:115], s[52:53], 0, v[114:115]
	v_mov_b32_e32 v203, v0
	v_lshl_add_u64 v[122:123], v[114:115], 0, v[202:203]
	s_mov_b64 s[16:17], 0x1000
	global_load_dwordx4 v[118:121], v[122:123], off
	global_load_dwordx4 v[114:117], v[122:123], off offset:16
	v_lshl_add_u64 v[124:125], v[122:123], 0, s[16:17]
	v_add_co_u32_e32 v122, vcc, 0x1000, v122
	s_nop 1
	v_addc_co_u32_e32 v123, vcc, 0, v123, vcc
	global_load_dwordx4 v[126:129], v[122:123], off
	s_nop 0
	global_load_dwordx4 v[122:125], v[124:125], off offset:16
	s_branch .LBB0_605
